# v34: phase-2 log-sigmoid tail in log2 units: log_alpha/16*log2e = fma(min(x,0), log2e/16, -log2(1+exp(-|x|))/16); drops the ln2 conversion chain (52 instructions per item), f32
# speedup vs baseline: 1.0073x; 1.0047x over previous
; #define LAS __attribute__((address_space(3)))
; __device__ __forceinline__ void phase_gla_pre(const Params& P, LAS unsigned char* lds, bool dry) {
;     ...
;         for (int tt = 0; tt < 4; ++tt) {
;             bf16x8 ahi = (bf16x8){0, 0, 0, 0, 0, 0, 0, 0}, alo = ahi;
;             if (g < 2) { const f32x4 l0 = *(const LAS f32x4*)(Llr + (16 * tt + fr) * 16 + 8 * g), l1 = *(const LAS f32x4*)(Llr + (16 * tt + fr) * 16 + 8 * g + 4); split8(l0, l1, ahi, alo); }
;             f32x4 acc = (f32x4){bg, bg, bg, bg};
;             acc = __builtin_amdgcn_mfma_f32_16x16x32_bf16(alo, bhi, acc, 0, 0, 0); acc = __builtin_amdgcn_mfma_f32_16x16x32_bf16(ahi, blo, acc, 0, 0, 0); acc = __builtin_amdgcn_mfma_f32_16x16x32_bf16(ahi, bhi, acc, 0, 0, 0);
;             float pr[4];
; #pragma unroll
;             for (int r = 0; r < 4; ++r) { const float lg = acc[r]; const float ls = fminf(lg, 0.f) - __logf(1.0f + __expf(-fabsf(lg))); pr[r] = ls * (1.0f / 16.0f) + (r ? pr[r - 1] : 0.f); }
;             const float T = pr[3];
;             const float u1 = __shfl_up(T, 16), s1 = T + (g >= 1 ? u1 : 0.f);
;             const float u2 = __shfl_up(s1, 32), s2 = s1 + (g >= 2 ? u2 : 0.f);
;             const float base = run + (s2 - T); run += __shfl(s2, 48 + fr);
; #pragma unroll
;             for (int r = 0; r < 4; ++r) *(LAS float*)(Lb + (16 * tt + 4 * g + r) * BP + (16 * w + fr) * 4) = base + pr[r];
.Lp2_nowait1:
	v_mov_b32_e32 v140, v20
	v_mov_b32_e32 v141, v21
	v_mov_b32_e32 v142, v22
	v_mov_b32_e32 v143, v23
	v_mov_b32_e32 v144, v24
	v_mov_b32_e32 v145, v25
	v_mov_b32_e32 v146, v26
	v_mov_b32_e32 v147, v27
	v_mov_b32_e32 v148, v28
	s_and_b32 s98, s38, 0xff
	s_cselect_b32 s98, 0, 1
	v_mov_b32_e32 v29, v28
	v_mov_b32_e32 v30, v28
	v_mov_b32_e32 v31, v28
	s_nop 1
	v_mfma_f32_16x16x32_bf16 v[32:35], v[100:103], v[20:23], v[28:31]
	v_mfma_f32_16x16x32_bf16 v[32:35], v[104:107], v[24:27], v[32:35]
	v_mfma_f32_16x16x32_bf16 v[32:35], v[104:107], v[20:23], v[32:35]
	s_nop 7
	v_min_f32_e32 v36, 0, v32
	v_mul_f32_e64 v32, |v32|, s89
	v_exp_f32_e32 v32, v32
	v_mul_f32_e64 v37, |v33|, s89
	v_exp_f32_e32 v37, v37
	v_add_f32_e32 v32, 1.0, v32
	v_add_f32_e32 v37, 1.0, v37
	v_log_f32_e32 v32, v32
	v_log_f32_e32 v37, v37
	v_mul_f32_e32 v39, 0x3d800000, v32
	v_min_f32_e32 v33, 0, v33
	v_fma_f32 v32, v36, s93, -v39
	v_mul_f32_e32 v36, 0x3d800000, v37
	v_mul_f32_e64 v37, |v34|, s89
	v_exp_f32_e32 v37, v37
	v_fma_f32 v33, v33, s93, -v36
	v_add_f32_e32 v36, 1.0, v37
	s_nop 1
	v_log_f32_e32 v36, v36
	v_add_f32_e32 v37, v33, v32
	v_min_f32_e32 v33, 0, v34
	v_mul_f32_e32 v34, 0x3d800000, v36
	s_nop 0
	v_mul_f32_e64 v36, |v35|, s89
	v_exp_f32_e32 v36, v36
	v_fma_f32 v33, v33, s93, -v34
	v_add_u32_e32 v38, 0x8800, v98
	v_add_f32_e32 v34, 1.0, v36
	s_nop 1
	v_log_f32_e32 v34, v34
	v_add_f32_e32 v36, v33, v37
	v_min_f32_e32 v33, 0, v35
	v_mul_f32_e32 v35, 0x3d800000, v34
	s_nop 1
	v_fma_f32 v33, v33, s93, -v35
	v_add_f32_e32 v34, v33, v36
	ds_bpermute_b32 v33, v83, v34
	s_waitcnt lgkmcnt(0)
	v_cndmask_b32_e64 v33, v33, 0, s[8:9]
	v_add_f32_e32 v33, v33, v34
	ds_bpermute_b32 v35, v84, v33
	s_waitcnt lgkmcnt(0)
	v_cndmask_b32_e64 v35, 0, v35, s[10:11]
	v_add_f32_e32 v33, v35, v33
	v_sub_f32_e32 v35, v33, v34
	ds_bpermute_b32 v33, v85, v33
	v_add_f32_e32 v35, 0, v35
	v_add_f32_e32 v32, v32, v35
	v_add_f32_e32 v37, v37, v35
	ds_write2_b32 v38, v32, v37 offset1:132
	v_add_f32_e32 v32, v36, v35
	v_add_f32_e32 v34, v34, v35
	v_add_u32_e32 v35, 0x8c00, v98
	ds_write2_b32 v35, v32, v34 offset0:8 offset1:140
	v_mov_b32_e32 v108, 0
	v_mov_b32_e32 v109, 0
	v_mov_b32_e32 v110, 0
	v_mov_b32_e32 v111, 0
	v_mov_b32_e32 v112, 0
	v_mov_b32_e32 v113, 0
	v_mov_b32_e32 v114, 0
	v_mov_b32_e32 v115, 0
	s_and_saveexec_b64 s[36:37], s[6:7]
	s_cbranch_execz .LBB0_488
	ds_read_b128 v[34:37], v96 offset:1024
	ds_read_b128 v[38:41], v96 offset:1040
	s_waitcnt lgkmcnt(1)
	v_cvt_pk_bf16_f32 v112, v34, v35
	v_lshlrev_b32_e32 v132, 16, v112
	v_and_b32_e32 v133, 0xffff0000, v112
	v_pk_add_f32 v[34:35], v[34:35], v[132:133] neg_lo:[0,1] neg_hi:[0,1]
	v_cvt_pk_bf16_f32 v113, v36, v37
	v_lshlrev_b32_e32 v134, 16, v113
	v_and_b32_e32 v135, 0xffff0000, v113
	v_pk_add_f32 v[36:37], v[36:37], v[134:135] neg_lo:[0,1] neg_hi:[0,1]
	s_waitcnt lgkmcnt(0)
	v_cvt_pk_bf16_f32 v114, v38, v39
	v_lshlrev_b32_e32 v136, 16, v114
	v_and_b32_e32 v137, 0xffff0000, v114
	v_pk_add_f32 v[38:39], v[38:39], v[136:137] neg_lo:[0,1] neg_hi:[0,1]
	v_cvt_pk_bf16_f32 v115, v40, v41
	v_lshlrev_b32_e32 v138, 16, v115
	v_and_b32_e32 v139, 0xffff0000, v115
	v_pk_add_f32 v[40:41], v[40:41], v[138:139] neg_lo:[0,1] neg_hi:[0,1]
	s_nop 0
	v_cvt_pk_bf16_f32 v111, v40, v41
	v_cvt_pk_bf16_f32 v110, v38, v39
	v_cvt_pk_bf16_f32 v109, v36, v37
	v_cvt_pk_bf16_f32 v108, v34, v35
.LBB0_488:
	s_or_b64 exec, exec, s[36:37]
	s_nop 0
	v_mfma_f32_16x16x32_bf16 v[34:37], v[108:111], v[20:23], v[28:31]
	v_mfma_f32_16x16x32_bf16 v[34:37], v[112:115], v[24:27], v[34:37]
	v_mfma_f32_16x16x32_bf16 v[34:37], v[112:115], v[20:23], v[34:37]
	s_nop 7
	v_min_f32_e32 v38, 0, v34
	v_mul_f32_e64 v34, |v34|, s89
	v_exp_f32_e32 v34, v34
	v_mul_f32_e64 v39, |v35|, s89
	v_exp_f32_e32 v39, v39
	v_add_f32_e32 v34, 1.0, v34
	v_add_f32_e32 v39, 1.0, v39
	v_log_f32_e32 v34, v34
	v_log_f32_e32 v39, v39
	v_mul_f32_e32 v41, 0x3d800000, v34
	v_fma_f32 v34, v38, s93, -v41
	v_mul_f32_e32 v38, 0x3d800000, v39
	v_min_f32_e32 v35, 0, v35
	v_mul_f32_e64 v39, |v36|, s89
	v_exp_f32_e32 v39, v39
	v_fma_f32 v35, v35, s93, -v38
	v_add_f32_e32 v38, 1.0, v39
	v_min_f32_e32 v36, 0, v36
	v_log_f32_e32 v38, v38
	v_add_f32_e32 v35, v35, v34
	v_mul_f32_e32 v39, 0x3d800000, v38
	s_nop 1
	v_mov_b32_e32 v38, v39
	v_mul_f32_e64 v39, |v37|, s89
	v_exp_f32_e32 v39, v39
	v_fma_f32 v36, v36, s93, -v38
	v_add_f32_e32 v38, 1.0, v39
	v_min_f32_e32 v37, 0, v37
	v_add_f32_e32 v36, v36, v35
	v_log_f32_e32 v38, v38
	s_waitcnt lgkmcnt(2)
	v_add_f32_e32 v40, 0, v33
	v_mul_f32_e32 v39, 0x3d800000, v38
	s_nop 1
	v_fma_f32 v37, v37, s93, -v39
	v_add_f32_e32 v37, v37, v36
	ds_bpermute_b32 v38, v83, v37
	s_waitcnt lgkmcnt(0)
	v_cndmask_b32_e64 v38, v38, 0, s[8:9]
	v_add_f32_e32 v38, v38, v37
	ds_bpermute_b32 v39, v84, v38
	s_waitcnt lgkmcnt(0)
	v_cndmask_b32_e64 v33, 0, v39, s[10:11]
	v_add_f32_e32 v33, v33, v38
	v_sub_f32_e32 v38, v33, v37
	ds_bpermute_b32 v41, v85, v33
	v_add_f32_e32 v38, v40, v38
	v_add_f32_e32 v33, v34, v38
	v_add_f32_e32 v34, v35, v38
	v_add_u32_e32 v35, 0xa800, v98
	ds_write2_b32 v35, v33, v34 offset0:64 offset1:196
	v_add_f32_e32 v33, v36, v38
	v_add_f32_e32 v34, v37, v38
	v_add_u32_e32 v35, 0xac00, v98
	ds_write2_b32 v35, v33, v34 offset0:72 offset1:204
	v_mov_b32_e32 v116, 0
	v_mov_b32_e32 v117, 0
	v_mov_b32_e32 v118, 0
	v_mov_b32_e32 v119, 0
	v_mov_b32_e32 v120, 0
	v_mov_b32_e32 v121, 0
	v_mov_b32_e32 v122, 0
	v_mov_b32_e32 v123, 0
	s_and_saveexec_b64 s[36:37], s[6:7]
	s_cbranch_execz .LBB0_490
	ds_read_b128 v[32:35], v96 offset:2048
	ds_read_b128 v[36:39], v96 offset:2064
	s_waitcnt lgkmcnt(1)
	v_cvt_pk_bf16_f32 v120, v32, v33
	v_lshlrev_b32_e32 v132, 16, v120
	v_and_b32_e32 v133, 0xffff0000, v120
	v_pk_add_f32 v[32:33], v[32:33], v[132:133] neg_lo:[0,1] neg_hi:[0,1]
	v_cvt_pk_bf16_f32 v121, v34, v35
	v_lshlrev_b32_e32 v134, 16, v121
	v_and_b32_e32 v135, 0xffff0000, v121
	v_pk_add_f32 v[34:35], v[34:35], v[134:135] neg_lo:[0,1] neg_hi:[0,1]
	s_waitcnt lgkmcnt(0)
	v_cvt_pk_bf16_f32 v122, v36, v37
	v_lshlrev_b32_e32 v136, 16, v122
	v_and_b32_e32 v137, 0xffff0000, v122
	v_pk_add_f32 v[36:37], v[36:37], v[136:137] neg_lo:[0,1] neg_hi:[0,1]
	v_cvt_pk_bf16_f32 v123, v38, v39
	v_lshlrev_b32_e32 v138, 16, v123
	v_and_b32_e32 v139, 0xffff0000, v123
	v_pk_add_f32 v[38:39], v[38:39], v[138:139] neg_lo:[0,1] neg_hi:[0,1]
	s_nop 0
	v_cvt_pk_bf16_f32 v119, v38, v39
	v_cvt_pk_bf16_f32 v118, v36, v37
	v_cvt_pk_bf16_f32 v117, v34, v35
	v_cvt_pk_bf16_f32 v116, v32, v33
; #define LAS __attribute__((address_space(3)))
; __device__ __forceinline__ void phase_gla_pre(const Params& P, LAS unsigned char* lds, bool dry) {
;     ...
;         for (int tt = 0; tt < 4; ++tt) {
;             bf16x8 ahi = (bf16x8){0, 0, 0, 0, 0, 0, 0, 0}, alo = ahi;
;             if (g < 2) { const f32x4 l0 = *(const LAS f32x4*)(Llr + (16 * tt + fr) * 16 + 8 * g), l1 = *(const LAS f32x4*)(Llr + (16 * tt + fr) * 16 + 8 * g + 4); split8(l0, l1, ahi, alo); }
;             f32x4 acc = (f32x4){bg, bg, bg, bg};
;             acc = __builtin_amdgcn_mfma_f32_16x16x32_bf16(alo, bhi, acc, 0, 0, 0); acc = __builtin_amdgcn_mfma_f32_16x16x32_bf16(ahi, blo, acc, 0, 0, 0); acc = __builtin_amdgcn_mfma_f32_16x16x32_bf16(ahi, bhi, acc, 0, 0, 0);
;             float pr[4];
; #pragma unroll
;             for (int r = 0; r < 4; ++r) { const float lg = acc[r]; const float ls = fminf(lg, 0.f) - __logf(1.0f + __expf(-fabsf(lg))); pr[r] = ls * (1.0f / 16.0f) + (r ? pr[r - 1] : 0.f); }
;             const float T = pr[3];
;             const float u1 = __shfl_up(T, 16), s1 = T + (g >= 1 ? u1 : 0.f);
;             const float u2 = __shfl_up(s1, 32), s2 = s1 + (g >= 2 ? u2 : 0.f);
;             const float base = run + (s2 - T); run += __shfl(s2, 48 + fr);
; #pragma unroll
;             for (int r = 0; r < 4; ++r) *(LAS float*)(Lb + (16 * tt + 4 * g + r) * BP + (16 * w + fr) * 4) = base + pr[r];
;         }
;         __syncthreads();
.LBB0_490:
	s_or_b64 exec, exec, s[36:37]
	s_nop 0
	v_mfma_f32_16x16x32_bf16 v[32:35], v[116:119], v[20:23], v[28:31]
	s_waitcnt lgkmcnt(2)
	v_add_f32_e32 v40, v40, v41
	v_mfma_f32_16x16x32_bf16 v[32:35], v[120:123], v[24:27], v[32:35]
	v_mfma_f32_16x16x32_bf16 v[32:35], v[120:123], v[20:23], v[32:35]
	s_nop 7
	v_min_f32_e32 v36, 0, v32
	v_mul_f32_e64 v32, |v32|, s89
	v_exp_f32_e32 v32, v32
	v_mul_f32_e64 v37, |v33|, s89
	v_exp_f32_e32 v37, v37
	v_add_f32_e32 v32, 1.0, v32
	v_add_f32_e32 v37, 1.0, v37
	v_log_f32_e32 v32, v32
	v_log_f32_e32 v37, v37
	v_mul_f32_e32 v39, 0x3d800000, v32
	v_fma_f32 v32, v36, s93, -v39
	v_mul_f32_e32 v36, 0x3d800000, v37
	v_min_f32_e32 v33, 0, v33
	v_mul_f32_e64 v37, |v34|, s89
	v_exp_f32_e32 v37, v37
	v_fma_f32 v33, v33, s93, -v36
	v_add_f32_e32 v36, 1.0, v37
	v_min_f32_e32 v34, 0, v34
	v_log_f32_e32 v36, v36
	v_add_f32_e32 v33, v33, v32
	v_mul_f32_e32 v37, 0x3d800000, v36
	s_nop 1
	v_mov_b32_e32 v36, v37
	v_mul_f32_e64 v37, |v35|, s89
	v_exp_f32_e32 v37, v37
	v_fma_f32 v34, v34, s93, -v36
	v_add_f32_e32 v36, 1.0, v37
	v_min_f32_e32 v35, 0, v35
	v_add_f32_e32 v34, v34, v33
	v_log_f32_e32 v36, v36
	s_nop 0
	v_mul_f32_e32 v37, 0x3d800000, v36
	s_nop 1
	v_fma_f32 v35, v35, s93, -v37
	v_add_f32_e32 v35, v35, v34
	ds_bpermute_b32 v36, v83, v35
	s_waitcnt lgkmcnt(0)
	v_cndmask_b32_e64 v36, v36, 0, s[8:9]
	v_add_f32_e32 v36, v36, v35
	ds_bpermute_b32 v37, v84, v36
	s_waitcnt lgkmcnt(0)
	v_cndmask_b32_e64 v37, 0, v37, s[10:11]
	v_add_f32_e32 v36, v37, v36
	v_sub_f32_e32 v37, v36, v35
	ds_bpermute_b32 v41, v85, v36
	v_add_f32_e32 v37, v40, v37
	v_add_f32_e32 v32, v32, v37
	v_add_f32_e32 v33, v33, v37
	v_add_u32_e32 v36, 0xca00, v98
	ds_write2_b32 v36, v32, v33 offset1:132
	v_add_f32_e32 v32, v34, v37
	v_add_f32_e32 v33, v35, v37
	v_add_u32_e32 v34, 0xce00, v98
	ds_write2_b32 v34, v32, v33 offset0:8 offset1:140
	v_mov_b32_e32 v124, 0
	v_mov_b32_e32 v125, 0
	v_mov_b32_e32 v126, 0
	v_mov_b32_e32 v127, 0
	v_mov_b32_e32 v128, 0
	v_mov_b32_e32 v129, 0
	v_mov_b32_e32 v130, 0
	v_mov_b32_e32 v131, 0
	s_and_saveexec_b64 s[36:37], s[6:7]
	s_cbranch_execz .LBB0_492
	ds_read_b128 v[32:35], v96 offset:3072
	ds_read_b128 v[36:39], v96 offset:3088
	s_waitcnt lgkmcnt(1)
	v_cvt_pk_bf16_f32 v128, v32, v33
	v_lshlrev_b32_e32 v132, 16, v128
	v_and_b32_e32 v133, 0xffff0000, v128
	v_pk_add_f32 v[32:33], v[32:33], v[132:133] neg_lo:[0,1] neg_hi:[0,1]
	v_cvt_pk_bf16_f32 v129, v34, v35
	v_lshlrev_b32_e32 v134, 16, v129
	v_and_b32_e32 v135, 0xffff0000, v129
	v_pk_add_f32 v[34:35], v[34:35], v[134:135] neg_lo:[0,1] neg_hi:[0,1]
	s_waitcnt lgkmcnt(0)
	v_cvt_pk_bf16_f32 v130, v36, v37
	v_lshlrev_b32_e32 v136, 16, v130
	v_and_b32_e32 v137, 0xffff0000, v130
	v_pk_add_f32 v[36:37], v[36:37], v[136:137] neg_lo:[0,1] neg_hi:[0,1]
	v_cvt_pk_bf16_f32 v131, v38, v39
	v_lshlrev_b32_e32 v138, 16, v131
	v_and_b32_e32 v139, 0xffff0000, v131
	v_pk_add_f32 v[38:39], v[38:39], v[138:139] neg_lo:[0,1] neg_hi:[0,1]
	s_nop 0
	v_cvt_pk_bf16_f32 v127, v38, v39
	v_cvt_pk_bf16_f32 v126, v36, v37
	v_cvt_pk_bf16_f32 v125, v34, v35
	v_cvt_pk_bf16_f32 v124, v32, v33
.LBB0_492:
	s_or_b64 exec, exec, s[36:37]
	s_nop 0
	v_mfma_f32_16x16x32_bf16 v[28:31], v[124:127], v[20:23], v[28:31]
	v_and_b32_e32 v111, 0xffff0000, v5
	v_and_b32_e32 v110, 0xffff0000, v4
	v_and_b32_e32 v117, 0xffff0000, v13
	v_mfma_f32_16x16x32_bf16 v[24:27], v[128:131], v[24:27], v[28:31]
	v_and_b32_e32 v116, 0xffff0000, v12
	v_and_b32_e32 v121, 0xffff0000, v7
	v_and_b32_e32 v120, 0xffff0000, v6
	v_mfma_f32_16x16x32_bf16 v[20:23], v[128:131], v[20:23], v[24:27]
	v_and_b32_e32 v127, 0xffff0000, v17
	v_and_b32_e32 v126, 0xffff0000, v16
	v_lshlrev_b32_e32 v125, 16, v17
	v_lshlrev_b32_e32 v124, 16, v16
	v_lshlrev_b32_e32 v133, 16, v11
	s_nop 2
	v_min_f32_e32 v24, 0, v20
	v_mul_f32_e64 v20, |v20|, s89
	v_exp_f32_e32 v20, v20
	v_mul_f32_e64 v25, |v21|, s89
	v_exp_f32_e32 v25, v25
	v_add_f32_e32 v20, 1.0, v20
	v_add_f32_e32 v25, 1.0, v25
	v_log_f32_e32 v20, v20
	v_log_f32_e32 v25, v25
	v_mul_f32_e32 v27, 0x3d800000, v20
	v_fma_f32 v20, v24, s93, -v27
	v_mul_f32_e32 v24, 0x3d800000, v25
	v_min_f32_e32 v21, 0, v21
	v_mul_f32_e64 v25, |v22|, s89
	v_exp_f32_e32 v25, v25
	v_fma_f32 v21, v21, s93, -v24
	v_add_f32_e32 v24, 1.0, v25
	v_min_f32_e32 v22, 0, v22
	v_log_f32_e32 v24, v24
	v_add_f32_e32 v21, v21, v20
	v_lshlrev_b32_e32 v132, 16, v10
	v_mul_f32_e32 v25, 0x3d800000, v24
	v_and_b32_e32 v135, 0xffff0000, v11
	v_and_b32_e32 v134, 0xffff0000, v10
	v_mov_b32_e32 v24, v25
	v_mul_f32_e64 v25, |v23|, s89
	v_exp_f32_e32 v25, v25
	v_fma_f32 v22, v22, s93, -v24
	v_add_f32_e32 v24, 1.0, v25
	v_min_f32_e32 v23, 0, v23
	v_add_f32_e32 v22, v22, v21
	v_log_f32_e32 v24, v24
	s_waitcnt lgkmcnt(2)
	v_add_f32_e32 v26, v40, v41
	s_and_b32 s74, s1, 0xfc0
	s_ashr_i32 s83, s82, 31
	v_mul_f32_e32 v25, 0x3d800000, v24
	s_nop 1
	v_fma_f32 v23, v23, s93, -v25
	v_add_f32_e32 v23, v23, v22
	ds_bpermute_b32 v24, v83, v23
	s_lshl_b64 s[36:37], s[82:83], 20
	s_waitcnt lgkmcnt(0)
	v_cndmask_b32_e64 v24, v24, 0, s[8:9]
	v_add_f32_e32 v24, v24, v23
	ds_bpermute_b32 v25, v84, v24
	s_waitcnt lgkmcnt(0)
	v_cndmask_b32_e64 v25, 0, v25, s[10:11]
	v_add_f32_e32 v24, v25, v24
	v_sub_f32_e32 v24, v24, v23
	v_add_f32_e32 v24, v26, v24
	v_add_f32_e32 v20, v20, v24
	v_add_f32_e32 v21, v21, v24
	v_add_u32_e32 v25, 0xea00, v98
	ds_write2_b32 v25, v20, v21 offset0:64 offset1:196
	v_add_f32_e32 v20, v22, v24
	v_add_f32_e32 v21, v23, v24
	v_add_u32_e32 v22, 0xee00, v98
	ds_write2_b32 v22, v20, v21 offset0:72 offset1:204
	v_add_u32_e32 v22, s94, v87
	s_waitcnt lgkmcnt(0)
	s_barrier
; #define LAS __attribute__((address_space(3)))
; __device__ __forceinline__ float bflo(unsigned w) { return __uint_as_float(w << 16); }
; __device__ __forceinline__ float bfhi(unsigned w) { return __uint_as_float(w & 0xffff0000u); }
; __device__ __forceinline__ void phase_gla_pre(const Params& P, LAS unsigned char* lds, bool dry) {
;     ...
;             f32x4 bb[4], bm[4], bl[4];
; #pragma unroll
;             for (int i = 0; i < 4; ++i) { bb[i] = *(const LAS f32x4*)(Lb + te * BP + (16 * kc + 4 * i) * 4); bm[i] = *(const LAS f32x4*)(Lb + 31 * BP + (16 * kc + 4 * i) * 4); bl[i] = *(const LAS f32x4*)(Lb + 63 * BP + (16 * kc + 4 * i) * 4); }
;             unsigned oqi[8], oki[8], oqd[8], oks[8];
; #pragma unroll
;             for (int e2 = 0; e2 < 8; ++e2) {
;                 const unsigned qw = e2 < 4 ? rq[0][e2] : rq[1][e2 - 4], kw = e2 < 4 ? rk[0][e2] : rk[1][e2 - 4];
;                 float vqi[2], vki[2], vqd[2], vks[2];
; #pragma unroll
;                 for (int hh = 0; hh < 2; ++hh) {
;                     const int e = 2 * e2 + hh; const float bv = bb[e >> 2][e & 3], bmv = bm[e >> 2][e & 3], blv = bl[e >> 2][e & 3];
;                     const float qv = hh ? bfhi(qw) : bflo(qw), kv = hh ? bfhi(kw) : bflo(kw);
;                     const float e1 = __expf(bv - bmv);
;                     vqi[hh] = qv * e1; vki[hh] = kv * __builtin_amdgcn_rcpf(e1); vqd[hh] = qv * __expf(bv); vks[hh] = kv * __expf(blv - bv);
;                 }
	v_add_u32_e32 v20, v86, v87
	v_add_u32_e32 v21, 0, v87
	ds_read_b128 v[32:35], v22
	ds_read_b128 v[24:27], v89
	ds_read_b128 v[60:63], v21 offset:51184
	ds_read_b128 v[64:67], v20 offset:34816
	ds_read_b128 v[74:77], v20 offset:34832
	ds_read_b128 v[44:47], v20 offset:34848
	ds_read_b128 v[36:39], v20 offset:34864
	ds_read_b128 v[100:103], v21 offset:51200
	s_waitcnt lgkmcnt(4)
	v_sub_f32_e32 v61, v65, v61
	v_sub_f32_e32 v63, v67, v63
	v_exp_f32_e32 v72, v61
	v_sub_f32_e32 v61, v32, v64
	v_exp_f32_e32 v73, v63
	v_exp_f32_e32 v78, v61
	v_sub_f32_e32 v20, v64, v60
	v_exp_f32_e32 v108, v65
	v_sub_f32_e32 v61, v66, v62
	v_sub_f32_e32 v62, v33, v65
	v_sub_f32_e32 v63, v34, v66
	v_exp_f32_e32 v60, v20
	v_exp_f32_e32 v70, v64
	v_rcp_f32_e32 v64, v72
	v_exp_f32_e32 v61, v61
	v_exp_f32_e32 v71, v66
	v_rcp_f32_e32 v65, v73
	v_exp_f32_e32 v79, v63
	v_exp_f32_e32 v109, v67
	v_sub_f32_e32 v63, v35, v67
	v_lshlrev_b32_e32 v67, 16, v5
	v_lshlrev_b32_e32 v66, 16, v4
	v_pk_mul_f32 v[112:113], v[60:61], v[66:67]
	v_pk_mul_f32 v[114:115], v[72:73], v[110:111]
	v_pk_mul_f32 v[72:73], v[64:65], v[116:117]
	v_pk_mul_f32 v[64:65], v[70:71], v[66:67]
	s_waitcnt lgkmcnt(0)
	v_sub_f32_e32 v66, v74, v100
	v_exp_f32_e32 v70, v66
	v_pk_mul_f32 v[66:67], v[108:109], v[110:111]
	v_exp_f32_e32 v108, v74
	v_sub_f32_e32 v71, v75, v101
	v_exp_f32_e32 v100, v71
	v_sub_f32_e32 v71, v24, v74
	v_exp_f32_e32 v62, v62
	v_exp_f32_e32 v63, v63
	v_exp_f32_e32 v74, v71
	v_mov_b32_e32 v71, v75
	v_sub_f32_e32 v75, v25, v75
	v_exp_f32_e32 v118, v75
	v_pk_mul_f32 v[62:63], v[62:63], v[116:117]
	v_exp_f32_e32 v116, v71
	v_sub_f32_e32 v71, v76, v102
	v_exp_f32_e32 v109, v76
	v_sub_f32_e32 v75, v77, v103
	v_rcp_f32_e32 v68, v60
	v_rcp_f32_e32 v69, v61
	v_exp_f32_e32 v71, v71
	v_exp_f32_e32 v101, v75
	v_sub_f32_e32 v75, v26, v76
	v_exp_f32_e32 v117, v77
	v_sub_f32_e32 v76, v27, v77
	v_lshlrev_b32_e32 v61, 16, v13
	v_lshlrev_b32_e32 v60, 16, v12
	v_exp_f32_e32 v119, v76
	v_lshlrev_b32_e32 v77, 16, v7
	v_lshlrev_b32_e32 v76, 16, v6
	v_pk_mul_f32 v[68:69], v[68:69], v[60:61]
	v_pk_mul_f32 v[60:61], v[78:79], v[60:61]
	v_rcp_f32_e32 v78, v70
	v_rcp_f32_e32 v110, v100
	v_rcp_f32_e32 v79, v71
	v_rcp_f32_e32 v111, v101
	v_pk_mul_f32 v[70:71], v[70:71], v[76:77]
	v_pk_mul_f32 v[100:101], v[100:101], v[120:121]
	v_cvt_pk_bf16_f32 v224, v112, v114
	v_cvt_pk_bf16_f32 v222, v113, v115
	v_cvt_pk_bf16_f32 v102, v70, v100
	v_cvt_pk_bf16_f32 v103, v71, v101
	ds_read_b128 v[104:107], v21 offset:51216
	ds_read_b128 v[40:43], v21 offset:51232
	ds_read_b128 v[28:31], v90
	ds_read_b128 v[20:23], v91
	v_lshlrev_b32_e32 v71, 16, v15
	v_lshlrev_b32_e32 v70, 16, v14
	v_mov_b32_e32 v101, v222
	v_mov_b32_e32 v100, v224
	v_pk_mul_f32 v[114:115], v[78:79], v[70:71]
	s_waitcnt lgkmcnt(3)
	v_sub_f32_e32 v78, v44, v104
	v_sub_f32_e32 v105, v45, v105
	v_exp_f32_e32 v75, v75
	v_exp_f32_e32 v104, v78
	v_pk_mul_f32 v[78:79], v[116:117], v[120:121]
	v_exp_f32_e32 v116, v105
	v_mov_b32_e32 v105, v45
	s_waitcnt lgkmcnt(1)
	v_sub_f32_e32 v45, v29, v45
	v_and_b32_e32 v113, 0xffff0000, v15
	v_and_b32_e32 v112, 0xffff0000, v14
	v_exp_f32_e32 v120, v105
	v_sub_f32_e32 v105, v46, v106
	v_exp_f32_e32 v106, v45
	v_pk_mul_f32 v[110:111], v[110:111], v[112:113]
	v_pk_mul_f32 v[70:71], v[74:75], v[70:71]
	v_pk_mul_f32 v[74:75], v[118:119], v[112:113]
	v_exp_f32_e32 v113, v46
	v_sub_f32_e32 v45, v47, v107
	v_exp_f32_e32 v117, v45
	v_sub_f32_e32 v45, v30, v46
	v_exp_f32_e32 v121, v47
	v_sub_f32_e32 v46, v31, v47
	v_pk_mul_f32 v[76:77], v[108:109], v[76:77]
	v_exp_f32_e32 v112, v44
	v_exp_f32_e32 v105, v105
	v_exp_f32_e32 v107, v46
	v_rcp_f32_e32 v118, v116
	v_rcp_f32_e32 v119, v117
	v_sub_f32_e32 v44, v28, v44
	v_lshlrev_b32_e32 v47, 16, v9
	v_lshlrev_b32_e32 v46, 16, v8
	v_rcp_f32_e32 v108, v104
	v_rcp_f32_e32 v109, v105
	v_pk_mul_f32 v[104:105], v[104:105], v[46:47]
	v_pk_mul_f32 v[112:113], v[112:113], v[46:47]
	v_sub_f32_e32 v40, v36, v40
	v_pk_mul_f32 v[46:47], v[106:107], v[126:127]
	v_mov_b32_e32 v107, v36
	s_waitcnt lgkmcnt(0)
; #define LAS __attribute__((address_space(3)))
; __device__ __forceinline__ unsigned pk2(float lo, float hi) { return f2bf(lo) | (f2bf(hi) << 16); }
; __device__ __forceinline__ void phase_gla_pre(const Params& P, LAS unsigned char* lds, bool dry) {
;     ...
;                 }
;                 oqi[e2] = pk2(vqi[0], vqi[1]); oki[e2] = pk2(vki[0], vki[1]); oqd[e2] = pk2(vqd[0], vqd[1]); oks[e2] = pk2(vks[0], vks[1]);
;             }
;             *(LAS u32x4*)(Lqi + te * QP + 32 * kc) = (u32x4){oqi[0], oqi[1], oqi[2], oqi[3]}; *(LAS u32x4*)(Lqi + te * QP + 32 * kc + 16) = (u32x4){oqi[4], oqi[5], oqi[6], oqi[7]};
;             *(LAS u32x4*)(Lki + te * QP + 32 * kc) = (u32x4){oki[0], oki[1], oki[2], oki[3]}; *(LAS u32x4*)(Lki + te * QP + 32 * kc + 16) = (u32x4){oki[4], oki[5], oki[6], oki[7]};
;             if (!dry) {
;                 bf16_t* p_ = PJ + ((size_t)bh * SEQ + c * 64 + te) * 128 + 16 * kc;
;                 *(u32x4*)(p_ + T_Q) = (u32x4){oqd[0], oqd[1], oqd[2], oqd[3]}; *(u32x4*)(p_ + T_Q + 8) = (u32x4){oqd[4], oqd[5], oqd[6], oqd[7]};
;                 *(u32x4*)(p_ + T_K) = (u32x4){oks[0], oks[1], oks[2], oks[3]}; *(u32x4*)(p_ + T_K + 8) = (u32x4){oks[4], oks[5], oks[6], oks[7]};
;                 if (te == 63) {
; #pragma unroll
;                     for (int i = 0; i < 4; ++i) *(f32x4*)(DEC + (size_t)item * 128 + 16 * kc + 4 * i) = (f32x4){__expf(bl[i][0]), __expf(bl[i][1]), __expf(bl[i][2]), __expf(bl[i][3])};
;                 }
	v_sub_f32_e32 v36, v20, v36
	v_exp_f32_e32 v44, v44
	v_exp_f32_e32 v45, v45
	v_pk_mul_f32 v[118:119], v[118:119], v[126:127]
	v_exp_f32_e32 v126, v36
	v_sub_f32_e32 v41, v37, v41
	v_exp_f32_e32 v130, v37
	v_sub_f32_e32 v36, v38, v42
	v_pk_mul_f32 v[108:109], v[108:109], v[124:125]
	v_pk_mul_f32 v[44:45], v[44:45], v[124:125]
	v_exp_f32_e32 v124, v41
	v_exp_f32_e32 v41, v36
	v_sub_f32_e32 v36, v21, v37
	v_and_b32_e32 v123, 0xffff0000, v9
	v_and_b32_e32 v122, 0xffff0000, v8
	v_exp_f32_e32 v42, v36
	v_pk_mul_f32 v[116:117], v[116:117], v[122:123]
	v_pk_mul_f32 v[120:121], v[120:121], v[122:123]
	v_exp_f32_e32 v123, v38
	v_sub_f32_e32 v36, v39, v43
	v_exp_f32_e32 v125, v36
	v_sub_f32_e32 v36, v22, v38
	v_exp_f32_e32 v40, v40
	v_exp_f32_e32 v127, v36
	v_exp_f32_e32 v131, v39
	v_sub_f32_e32 v36, v23, v39
	v_rcp_f32_e32 v128, v124
	v_rcp_f32_e32 v129, v125
	v_exp_f32_e32 v43, v36
	v_pk_mul_f32 v[36:37], v[40:41], v[132:133]
	v_pk_mul_f32 v[38:39], v[124:125], v[134:135]
	v_rcp_f32_e32 v106, v40
	v_exp_f32_e32 v122, v107
	v_rcp_f32_e32 v107, v41
	v_cvt_pk_bf16_f32 v228, v104, v116
	v_cvt_pk_bf16_f32 v227, v105, v117
	v_cvt_pk_bf16_f32 v38, v36, v38
	v_cvt_pk_bf16_f32 v39, v37, v39
	v_mov_b32_e32 v37, v227
	v_mov_b32_e32 v36, v228
	ds_write_b128 v92, v[100:103]
	ds_write_b128 v92, v[36:39] offset:16
	v_cvt_pk_bf16_f32 v36, v68, v72
	v_cvt_pk_bf16_f32 v37, v69, v73
	v_lshlrev_b32_e32 v41, 16, v19
	v_lshlrev_b32_e32 v40, 16, v18
	v_cvt_pk_bf16_f32 v39, v115, v111
	v_cvt_pk_bf16_f32 v38, v114, v110
	v_and_b32_e32 v105, 0xffff0000, v19
	v_and_b32_e32 v104, 0xffff0000, v18
	v_pk_mul_f32 v[106:107], v[106:107], v[40:41]
	ds_write_b128 v92, v[36:39] offset:17408
	v_pk_mul_f32 v[116:117], v[128:129], v[104:105]
	s_nop 0
	v_cvt_pk_bf16_f32 v39, v107, v117
	v_cvt_pk_bf16_f32 v38, v106, v116
	v_cvt_pk_bf16_f32 v37, v109, v119
	v_cvt_pk_bf16_f32 v36, v108, v118
	ds_write_b128 v92, v[36:39] offset:17424
	v_lshl_add_u64 v[36:37], s[74:75], 0, v[48:49]
	v_lshlrev_b64 v[36:37], 8, v[36:37]
	v_lshl_add_u64 v[38:39], v[52:53], 0, s[36:37]
	v_lshl_add_u64 v[68:69], v[38:39], 0, v[36:37]
	v_cvt_pk_bf16_f32 v36, v64, v66
	v_cvt_pk_bf16_f32 v37, v65, v67
	s_brev_b32 s36, 16
	v_cvt_pk_bf16_f32 v39, v77, v79
	v_add_co_u32_e32 v64, vcc, s36, v68
	v_cvt_pk_bf16_f32 v38, v76, v78
	s_nop 0
	v_addc_co_u32_e32 v65, vcc, 0, v69, vcc
	v_pk_mul_f32 v[122:123], v[122:123], v[132:133]
	global_store_dwordx4 v[64:65], v[36:39], off
	v_pk_mul_f32 v[124:125], v[130:131], v[134:135]
	s_nop 0
	v_cvt_pk_bf16_f32 v39, v123, v125
	v_cvt_pk_bf16_f32 v38, v122, v124
	v_cvt_pk_bf16_f32 v37, v113, v121
	v_cvt_pk_bf16_f32 v36, v112, v120
	global_store_dwordx4 v[64:65], v[36:39], off offset:16
	s_nop 1
	s_nop 0
	v_cvt_pk_bf16_f32 v36, v60, v62
	v_cvt_pk_bf16_f32 v37, v61, v63
	v_cvt_pk_bf16_f32 v39, v71, v75
	v_add_co_u32_e32 v60, vcc, s95, v68
	v_pk_mul_f32 v[42:43], v[42:43], v[104:105]
	v_cvt_pk_bf16_f32 v38, v70, v74
	v_addc_co_u32_e32 v61, vcc, 0, v69, vcc
	v_pk_mul_f32 v[40:41], v[126:127], v[40:41]
	global_store_dwordx4 v[60:61], v[36:39], off
	s_nop 1
	v_cvt_pk_bf16_f32 v36, v44, v46
	v_cvt_pk_bf16_f32 v37, v45, v47
	v_cvt_pk_bf16_f32 v38, v40, v42
	v_cvt_pk_bf16_f32 v39, v41, v43
	global_store_dwordx4 v[60:61], v[36:39], off offset:16
	s_and_saveexec_b64 s[36:37], s[12:13]
	s_cbranch_execz .LBB0_494
	v_exp_f32_e32 v32, v32
	v_exp_f32_e32 v33, v33
	v_exp_f32_e32 v34, v34
	v_exp_f32_e32 v35, v35
	s_ashr_i32 s81, s80, 31
	v_exp_f32_e32 v24, v24
	v_exp_f32_e32 v25, v25
	v_exp_f32_e32 v26, v26
	v_exp_f32_e32 v27, v27
	s_lshl_b64 s[42:43], s[80:81], 9
	v_exp_f32_e32 v28, v28
	v_exp_f32_e32 v29, v29
	v_exp_f32_e32 v30, v30
	v_exp_f32_e32 v31, v31
	v_lshl_add_u64 v[36:37], v[54:55], 0, s[42:43]
	v_exp_f32_e32 v20, v20
	v_exp_f32_e32 v21, v21
	v_exp_f32_e32 v22, v22
	v_exp_f32_e32 v23, v23
	global_store_dwordx4 v[36:37], v[32:35], off
	global_store_dwordx4 v[36:37], v[24:27], off offset:16
	global_store_dwordx4 v[36:37], v[28:31], off offset:32
	global_store_dwordx4 v[36:37], v[20:23], off offset:48
